# adds: residual epilogues (Down/out0/out1) start with 12 x-tile loads in flight instead of 3 (more free register tuples in the pool)
# speedup vs baseline: 1.0024x; 1.0024x over previous
.LBB0_363:
	s_lshl_b32 s31, s11, 8
	s_min_i32 s20, s11, 0x100
	s_ashr_i32 s62, s20, 5
	s_add_i32 s63, s31, 0xffff0000
	s_cmpk_gt_i32 s11, 0xff
	s_cselect_b32 s11, s63, s31
	v_add_u32_e32 v146, s11, v1
	s_mul_i32 s62, s62, 0x9000
	s_cselect_b32 s23, s69, s65
	s_cselect_b32 s22, s70, s68
	s_cselect_b32 s21, s37, s49
	s_cselect_b32 s20, s33, s48
	v_lshl_or_b32 v147, s92, 8, v149
	v_lshlrev_b32_e32 v147, 2, v147
	v_lshl_add_u32 v146, v146, 12, v147
	v_add_u32_e32 v147, s62, v147
	v_add_co_u32_e32 v160, vcc, s75, v147
	v_mov_b32_e32 v161, s76
	s_nop 1
	v_addc_co_u32_e32 v161, vcc, 0, v161, vcc
	global_load_dwordx4 v[138:141], v[160:161], off
	global_load_dwordx4 v[142:145], v146, s[22:23]
	s_add_u32 s62, s22, 0x10000
	s_addc_u32 s63, s23, 0
	global_load_dwordx4 v[152:155], v146, s[62:63]
	s_add_u32 s62, s22, 0x20000
	s_addc_u32 s63, s23, 0
	global_load_dwordx4 v[156:159], v146, s[62:63]
	s_add_u32 s62, s22, 0x30000
	s_addc_u32 s63, s23, 0
	global_load_dwordx4 v[164:167], v146, s[62:63]
	s_add_u32 s62, s22, 0x80000
	s_addc_u32 s63, s23, 0
	global_load_dwordx4 v[168:171], v146, s[62:63]
	s_add_u32 s62, s22, 0x90000
	s_addc_u32 s63, s23, 0
	global_load_dwordx4 v[172:175], v146, s[62:63]
	s_add_u32 s62, s22, 0xa0000
	s_addc_u32 s63, s23, 0
	global_load_dwordx4 v[176:179], v146, s[62:63]
	s_add_u32 s62, s22, 0xb0000
	s_addc_u32 s63, s23, 0
	global_load_dwordx4 v[180:183], v146, s[62:63]
	global_load_dwordx4 v[184:187], v146, s[22:23] offset:64
	s_add_u32 s62, s22, 0x10000
	s_addc_u32 s63, s23, 0
	global_load_dwordx4 v[188:191], v146, s[62:63] offset:64
	s_add_u32 s62, s22, 0x20000
	s_addc_u32 s63, s23, 0
	global_load_dwordx4 v[192:195], v146, s[62:63] offset:64
	s_add_u32 s62, s22, 0x30000
	s_addc_u32 s63, s23, 0
	global_load_dwordx4 v[196:199], v146, s[62:63] offset:64
	s_waitcnt vmcnt(12)
	v_pk_mul_f32 v[138:139], v[138:139], 0.5 op_sel_hi:[1,0]
	v_pk_mul_f32 v[140:141], v[140:141], 0.5 op_sel_hi:[1,0]
	s_waitcnt vmcnt(11)
	v_pk_fma_f32 v[142:143], v[126:127], v[138:139], v[142:143]
	v_pk_fma_f32 v[144:145], v[128:129], v[140:141], v[144:145]
	global_store_dwordx4 v146, v[142:145], s[20:21]
	s_add_u32 s62, s22, 0x80000
	s_addc_u32 s63, s23, 0
	global_load_dwordx4 v[200:203], v146, s[62:63] offset:64
	s_waitcnt vmcnt(12)
	v_pk_fma_f32 v[152:153], v[122:123], v[138:139], v[152:153]
	v_pk_fma_f32 v[154:155], v[124:125], v[140:141], v[154:155]
	s_add_u32 vcc_lo, s20, 0x10000
	s_addc_u32 vcc_hi, s21, 0
	global_store_dwordx4 v146, v[152:155], vcc
	s_add_u32 s62, s22, 0x90000
	s_addc_u32 s63, s23, 0
	global_load_dwordx4 v[126:129], v146, s[62:63] offset:64
	s_waitcnt vmcnt(13)
	v_pk_fma_f32 v[156:157], v[118:119], v[138:139], v[156:157]
	v_pk_fma_f32 v[158:159], v[120:121], v[140:141], v[158:159]
	s_add_u32 vcc_lo, s20, 0x20000
	s_addc_u32 vcc_hi, s21, 0
	global_store_dwordx4 v146, v[156:159], vcc
	s_add_u32 s62, s22, 0xa0000
	s_addc_u32 s63, s23, 0
	global_load_dwordx4 v[142:145], v146, s[62:63] offset:64
	s_waitcnt vmcnt(14)
	v_pk_fma_f32 v[164:165], v[114:115], v[138:139], v[164:165]
	v_pk_fma_f32 v[166:167], v[116:117], v[140:141], v[166:167]
	s_add_u32 vcc_lo, s20, 0x30000
	s_addc_u32 vcc_hi, s21, 0
	global_store_dwordx4 v146, v[164:167], vcc
	global_load_dwordx4 v[122:125], v[160:161], off offset:64
	s_add_u32 s62, s22, 0xb0000
	s_addc_u32 s63, s23, 0
	global_load_dwordx4 v[152:155], v146, s[62:63] offset:64
	s_waitcnt vmcnt(16)
	v_pk_fma_f32 v[168:169], v[110:111], v[138:139], v[168:169]
	v_pk_fma_f32 v[170:171], v[112:113], v[140:141], v[170:171]
	s_add_u32 vcc_lo, s20, 0x80000
	s_addc_u32 vcc_hi, s21, 0
	global_store_dwordx4 v146, v[168:171], vcc
	global_load_dwordx4 v[118:121], v146, s[22:23] offset:512
	s_waitcnt vmcnt(17)
	v_pk_fma_f32 v[172:173], v[106:107], v[138:139], v[172:173]
	v_pk_fma_f32 v[174:175], v[108:109], v[140:141], v[174:175]
	s_add_u32 vcc_lo, s20, 0x90000
	s_addc_u32 vcc_hi, s21, 0
	global_store_dwordx4 v146, v[172:175], vcc
	s_add_u32 s62, s22, 0x10000
	s_addc_u32 s63, s23, 0
	global_load_dwordx4 v[156:159], v146, s[62:63] offset:512
	s_waitcnt vmcnt(18)
	v_pk_fma_f32 v[176:177], v[102:103], v[138:139], v[176:177]
	v_pk_fma_f32 v[178:179], v[104:105], v[140:141], v[178:179]
	s_add_u32 vcc_lo, s20, 0xa0000
	s_addc_u32 vcc_hi, s21, 0
	global_store_dwordx4 v146, v[176:179], vcc
	s_add_u32 s62, s22, 0x20000
	s_addc_u32 s63, s23, 0
	global_load_dwordx4 v[114:117], v146, s[62:63] offset:512
	s_waitcnt vmcnt(19)
	v_pk_fma_f32 v[180:181], v[98:99], v[138:139], v[180:181]
	v_pk_fma_f32 v[182:183], v[100:101], v[140:141], v[182:183]
	s_add_u32 vcc_lo, s20, 0xb0000
	s_addc_u32 vcc_hi, s21, 0
	global_store_dwordx4 v146, v[180:183], vcc
	s_add_u32 s62, s22, 0x30000
	s_addc_u32 s63, s23, 0
	global_load_dwordx4 v[164:167], v146, s[62:63] offset:512
	s_waitcnt vmcnt(9)
	v_pk_mul_f32 v[122:123], v[122:123], 0.5 op_sel_hi:[1,0]
	v_pk_mul_f32 v[124:125], v[124:125], 0.5 op_sel_hi:[1,0]
	s_waitcnt vmcnt(20)
	v_pk_fma_f32 v[184:185], v[94:95], v[122:123], v[184:185]
	v_pk_fma_f32 v[186:187], v[96:97], v[124:125], v[186:187]
	global_store_dwordx4 v146, v[184:187], s[20:21] offset:64
	s_add_u32 s62, s22, 0x80000
	s_addc_u32 s63, s23, 0
	global_load_dwordx4 v[110:113], v146, s[62:63] offset:512
	s_waitcnt vmcnt(21)
	v_pk_fma_f32 v[188:189], v[90:91], v[122:123], v[188:189]
	v_pk_fma_f32 v[190:191], v[92:93], v[124:125], v[190:191]
	s_add_u32 vcc_lo, s20, 0x10000
	s_addc_u32 vcc_hi, s21, 0
	global_store_dwordx4 v146, v[188:191], vcc offset:64
	s_add_u32 s62, s22, 0x90000
	s_addc_u32 s63, s23, 0
	global_load_dwordx4 v[168:171], v146, s[62:63] offset:512
	s_waitcnt vmcnt(22)
	v_pk_fma_f32 v[192:193], v[86:87], v[122:123], v[192:193]
	v_pk_fma_f32 v[194:195], v[88:89], v[124:125], v[194:195]
	s_add_u32 vcc_lo, s20, 0x20000
	s_addc_u32 vcc_hi, s21, 0
	global_store_dwordx4 v146, v[192:195], vcc offset:64
	s_add_u32 s62, s22, 0xa0000
	s_addc_u32 s63, s23, 0
	global_load_dwordx4 v[106:109], v146, s[62:63] offset:512
	s_waitcnt vmcnt(23)
	v_pk_fma_f32 v[196:197], v[82:83], v[122:123], v[196:197]
	v_pk_fma_f32 v[198:199], v[84:85], v[124:125], v[198:199]
	s_add_u32 vcc_lo, s20, 0x30000
	s_addc_u32 vcc_hi, s21, 0
	global_store_dwordx4 v146, v[196:199], vcc offset:64
	global_load_dwordx4 v[172:175], v[160:161], off offset:512
	s_add_u32 s62, s22, 0xb0000
	s_addc_u32 s63, s23, 0
	global_load_dwordx4 v[102:105], v146, s[62:63] offset:512
	s_waitcnt vmcnt(24)
	v_pk_fma_f32 v[200:201], v[78:79], v[122:123], v[200:201]
	v_pk_fma_f32 v[202:203], v[80:81], v[124:125], v[202:203]
	s_add_u32 vcc_lo, s20, 0x80000
	s_addc_u32 vcc_hi, s21, 0
	global_store_dwordx4 v146, v[200:203], vcc offset:64
	global_load_dwordx4 v[176:179], v146, s[22:23] offset:576
	s_waitcnt vmcnt(24)
	v_pk_fma_f32 v[126:127], v[74:75], v[122:123], v[126:127]
	v_pk_fma_f32 v[128:129], v[76:77], v[124:125], v[128:129]
	s_add_u32 vcc_lo, s20, 0x90000
	s_addc_u32 vcc_hi, s21, 0
	global_store_dwordx4 v146, v[126:129], vcc offset:64
	s_add_u32 s62, s22, 0x10000
	s_addc_u32 s63, s23, 0
	global_load_dwordx4 v[98:101], v146, s[62:63] offset:576
	s_waitcnt vmcnt(24)
	v_pk_fma_f32 v[142:143], v[70:71], v[122:123], v[142:143]
	v_pk_fma_f32 v[144:145], v[72:73], v[124:125], v[144:145]
	s_add_u32 vcc_lo, s20, 0xa0000
	s_addc_u32 vcc_hi, s21, 0
	global_store_dwordx4 v146, v[142:145], vcc offset:64
	s_add_u32 s62, s22, 0x20000
	s_addc_u32 s63, s23, 0
	global_load_dwordx4 v[180:183], v146, s[62:63] offset:576
	s_waitcnt vmcnt(23)
	v_pk_fma_f32 v[152:153], v[66:67], v[122:123], v[152:153]
	v_pk_fma_f32 v[154:155], v[68:69], v[124:125], v[154:155]
	s_add_u32 vcc_lo, s20, 0xb0000
	s_addc_u32 vcc_hi, s21, 0
	global_store_dwordx4 v146, v[152:155], vcc offset:64
	s_add_u32 s62, s22, 0x30000
	s_addc_u32 s63, s23, 0
	global_load_dwordx4 v[138:141], v146, s[62:63] offset:576
	s_waitcnt vmcnt(9)
	v_pk_mul_f32 v[172:173], v[172:173], 0.5 op_sel_hi:[1,0]
	v_pk_mul_f32 v[174:175], v[174:175], 0.5 op_sel_hi:[1,0]
	s_waitcnt vmcnt(23)
	v_pk_fma_f32 v[118:119], v[62:63], v[172:173], v[118:119]
	v_pk_fma_f32 v[120:121], v[64:65], v[174:175], v[120:121]
	global_store_dwordx4 v146, v[118:121], s[20:21] offset:512
	s_add_u32 s62, s22, 0x80000
	s_addc_u32 s63, s23, 0
	global_load_dwordx4 v[94:97], v146, s[62:63] offset:576
	s_waitcnt vmcnt(23)
	v_pk_fma_f32 v[156:157], v[58:59], v[172:173], v[156:157]
	v_pk_fma_f32 v[158:159], v[60:61], v[174:175], v[158:159]
	s_add_u32 vcc_lo, s20, 0x10000
	s_addc_u32 vcc_hi, s21, 0
	global_store_dwordx4 v146, v[156:159], vcc offset:512
	s_add_u32 s62, s22, 0x90000
	s_addc_u32 s63, s23, 0
	global_load_dwordx4 v[184:187], v146, s[62:63] offset:576
	s_waitcnt vmcnt(23)
	v_pk_fma_f32 v[114:115], v[54:55], v[172:173], v[114:115]
	v_pk_fma_f32 v[116:117], v[56:57], v[174:175], v[116:117]
	s_add_u32 vcc_lo, s20, 0x20000
	s_addc_u32 vcc_hi, s21, 0
	global_store_dwordx4 v146, v[114:117], vcc offset:512
	s_add_u32 s62, s22, 0xa0000
	s_addc_u32 s63, s23, 0
	global_load_dwordx4 v[90:93], v146, s[62:63] offset:576
	s_waitcnt vmcnt(23)
	v_pk_fma_f32 v[164:165], v[50:51], v[172:173], v[164:165]
	v_pk_fma_f32 v[166:167], v[52:53], v[174:175], v[166:167]
	s_add_u32 vcc_lo, s20, 0x30000
	s_addc_u32 vcc_hi, s21, 0
	global_store_dwordx4 v146, v[164:167], vcc offset:512
	global_load_dwordx4 v[188:191], v[160:161], off offset:576
	s_add_u32 s62, s22, 0xb0000
	s_addc_u32 s63, s23, 0
	global_load_dwordx4 v[86:89], v146, s[62:63] offset:576
	s_waitcnt vmcnt(24)
	v_pk_fma_f32 v[110:111], v[46:47], v[172:173], v[110:111]
	v_pk_fma_f32 v[112:113], v[48:49], v[174:175], v[112:113]
	s_add_u32 vcc_lo, s20, 0x80000
	s_addc_u32 vcc_hi, s21, 0
	global_store_dwordx4 v146, v[110:113], vcc offset:512
	s_waitcnt vmcnt(23)
	v_pk_fma_f32 v[168:169], v[42:43], v[172:173], v[168:169]
	v_pk_fma_f32 v[170:171], v[44:45], v[174:175], v[170:171]
	s_add_u32 vcc_lo, s20, 0x90000
	s_addc_u32 vcc_hi, s21, 0
	global_store_dwordx4 v146, v[168:171], vcc offset:512
	s_waitcnt vmcnt(22)
	v_pk_fma_f32 v[106:107], v[38:39], v[172:173], v[106:107]
	v_pk_fma_f32 v[108:109], v[40:41], v[174:175], v[108:109]
	s_add_u32 vcc_lo, s20, 0xa0000
	s_addc_u32 vcc_hi, s21, 0
	global_store_dwordx4 v146, v[106:109], vcc offset:512
	s_waitcnt vmcnt(20)
	v_pk_fma_f32 v[102:103], v[34:35], v[172:173], v[102:103]
	v_pk_fma_f32 v[104:105], v[36:37], v[174:175], v[104:105]
	s_add_u32 vcc_lo, s20, 0xb0000
	s_addc_u32 vcc_hi, s21, 0
	global_store_dwordx4 v146, v[102:105], vcc offset:512
	s_waitcnt vmcnt(5)
	v_pk_mul_f32 v[188:189], v[188:189], 0.5 op_sel_hi:[1,0]
	v_pk_mul_f32 v[190:191], v[190:191], 0.5 op_sel_hi:[1,0]
	s_waitcnt vmcnt(19)
	v_pk_fma_f32 v[176:177], v[30:31], v[188:189], v[176:177]
	v_pk_fma_f32 v[178:179], v[32:33], v[190:191], v[178:179]
	global_store_dwordx4 v146, v[176:179], s[20:21] offset:576
	s_waitcnt vmcnt(18)
	v_pk_fma_f32 v[98:99], v[26:27], v[188:189], v[98:99]
	v_pk_fma_f32 v[100:101], v[28:29], v[190:191], v[100:101]
	s_add_u32 vcc_lo, s20, 0x10000
	s_addc_u32 vcc_hi, s21, 0
	global_store_dwordx4 v146, v[98:101], vcc offset:576
	s_waitcnt vmcnt(17)
	v_pk_fma_f32 v[180:181], v[22:23], v[188:189], v[180:181]
	v_pk_fma_f32 v[182:183], v[24:25], v[190:191], v[182:183]
	s_add_u32 vcc_lo, s20, 0x20000
	s_addc_u32 vcc_hi, s21, 0
	global_store_dwordx4 v146, v[180:183], vcc offset:576
	s_waitcnt vmcnt(16)
	v_pk_fma_f32 v[138:139], v[18:19], v[188:189], v[138:139]
	v_pk_fma_f32 v[140:141], v[20:21], v[190:191], v[140:141]
	s_add_u32 vcc_lo, s20, 0x30000
	s_addc_u32 vcc_hi, s21, 0
	global_store_dwordx4 v146, v[138:141], vcc offset:576
	s_waitcnt vmcnt(15)
	v_pk_fma_f32 v[94:95], v[14:15], v[188:189], v[94:95]
	v_pk_fma_f32 v[96:97], v[16:17], v[190:191], v[96:97]
	s_add_u32 vcc_lo, s20, 0x80000
	s_addc_u32 vcc_hi, s21, 0
	global_store_dwordx4 v146, v[94:97], vcc offset:576
	s_waitcnt vmcnt(14)
	v_pk_fma_f32 v[184:185], v[10:11], v[188:189], v[184:185]
	v_pk_fma_f32 v[186:187], v[12:13], v[190:191], v[186:187]
	s_add_u32 vcc_lo, s20, 0x90000
	s_addc_u32 vcc_hi, s21, 0
	global_store_dwordx4 v146, v[184:187], vcc offset:576
	s_waitcnt vmcnt(13)
	v_pk_fma_f32 v[90:91], v[6:7], v[188:189], v[90:91]
	v_pk_fma_f32 v[92:93], v[8:9], v[190:191], v[92:93]
	s_add_u32 vcc_lo, s20, 0xa0000
	s_addc_u32 vcc_hi, s21, 0
	global_store_dwordx4 v146, v[90:93], vcc offset:576
	s_waitcnt vmcnt(11)
	v_pk_fma_f32 v[86:87], v[2:3], v[188:189], v[86:87]
	v_pk_fma_f32 v[88:89], v[4:5], v[190:191], v[88:89]
	s_add_u32 vcc_lo, s20, 0xb0000
	s_addc_u32 vcc_hi, s21, 0
	global_store_dwordx4 v146, v[86:89], vcc offset:576
	s_mov_b32 s11, 0
	s_mov_b64 s[62:63], 0xb0000
	s_mov_b64 s[20:21], -1
	s_and_b64 vcc, exec, s[0:1]
	s_cbranch_vccnz .LBB0_351
	s_andn2_b64 vcc, exec, s[14:15]
	s_cbranch_vccnz .LBB0_350
	s_barrier
	s_branch .LBB0_350

.LBB0_1015:
	s_lshl_b32 s20, s11, 8
	s_min_i32 s18, s11, 0x100
	s_ashr_i32 s21, s18, 5
	s_add_i32 s31, s20, 0xffff0000
	s_cmpk_gt_i32 s11, 0xff
	s_cselect_b32 s11, s31, s20
	v_add_u32_e32 v154, s11, v1
	v_lshl_or_b32 v155, s10, 8, v147
	s_mul_i32 s21, s21, 0x9000
	s_cselect_b32 s19, s37, s49
	s_cselect_b32 s18, s33, s48
	v_lshlrev_b32_e32 v155, 2, v155
	v_lshl_add_u32 v154, v154, 12, v155
	v_add_u32_e32 v155, s21, v155
	v_readlane_b32 s10, v255, 11
	v_readlane_b32 s20, v255, 13
	s_nop 1
	v_add_co_u32_e32 v156, vcc, s10, v155
	v_mov_b32_e32 v157, s20
	s_nop 1
	v_addc_co_u32_e32 v157, vcc, 0, v157, vcc
	global_load_dwordx4 v[130:133], v[156:157], off
	global_load_dwordx4 v[142:145], v154, s[18:19]
	s_add_u32 s10, s18, 0x10000
	s_addc_u32 s11, s19, 0
	global_load_dwordx4 v[150:153], v154, s[10:11]
	s_add_u32 s10, s18, 0x20000
	s_addc_u32 s11, s19, 0
	global_load_dwordx4 v[158:161], v154, s[10:11]
	s_add_u32 s10, s18, 0x30000
	s_addc_u32 s11, s19, 0
	global_load_dwordx4 v[162:165], v154, s[10:11]
	s_add_u32 s10, s18, 0x80000
	s_addc_u32 s11, s19, 0
	global_load_dwordx4 v[166:169], v154, s[10:11]
	s_add_u32 s10, s18, 0x90000
	s_addc_u32 s11, s19, 0
	global_load_dwordx4 v[170:173], v154, s[10:11]
	s_add_u32 s10, s18, 0xa0000
	s_addc_u32 s11, s19, 0
	global_load_dwordx4 v[174:177], v154, s[10:11]
	s_add_u32 s10, s18, 0xb0000
	s_addc_u32 s11, s19, 0
	global_load_dwordx4 v[178:181], v154, s[10:11]
	global_load_dwordx4 v[182:185], v154, s[18:19] offset:64
	s_add_u32 s10, s18, 0x10000
	s_addc_u32 s11, s19, 0
	global_load_dwordx4 v[186:189], v154, s[10:11] offset:64
	s_add_u32 s10, s18, 0x20000
	s_addc_u32 s11, s19, 0
	global_load_dwordx4 v[190:193], v154, s[10:11] offset:64
	s_add_u32 s10, s18, 0x30000
	s_addc_u32 s11, s19, 0
	global_load_dwordx4 v[194:197], v154, s[10:11] offset:64
	s_waitcnt vmcnt(12)
	s_waitcnt vmcnt(11)
	v_pk_fma_f32 v[142:143], v[126:127], v[130:131], v[142:143]
	v_pk_fma_f32 v[144:145], v[128:129], v[132:133], v[144:145]
	global_store_dwordx4 v154, v[142:145], s[18:19]
	s_add_u32 s10, s18, 0x80000
	s_addc_u32 s11, s19, 0
	global_load_dwordx4 v[198:201], v154, s[10:11] offset:64
	s_waitcnt vmcnt(12)
	v_pk_fma_f32 v[150:151], v[122:123], v[130:131], v[150:151]
	v_pk_fma_f32 v[152:153], v[124:125], v[132:133], v[152:153]
	s_add_u32 vcc_lo, s18, 0x10000
	s_addc_u32 vcc_hi, s19, 0
	global_store_dwordx4 v154, v[150:153], vcc
	s_add_u32 s10, s18, 0x90000
	s_addc_u32 s11, s19, 0
	global_load_dwordx4 v[126:129], v154, s[10:11] offset:64
	s_waitcnt vmcnt(13)
	v_pk_fma_f32 v[158:159], v[118:119], v[130:131], v[158:159]
	v_pk_fma_f32 v[160:161], v[120:121], v[132:133], v[160:161]
	s_add_u32 vcc_lo, s18, 0x20000
	s_addc_u32 vcc_hi, s19, 0
	global_store_dwordx4 v154, v[158:161], vcc
	s_add_u32 s10, s18, 0xa0000
	s_addc_u32 s11, s19, 0
	global_load_dwordx4 v[142:145], v154, s[10:11] offset:64
	s_waitcnt vmcnt(14)
	v_pk_fma_f32 v[162:163], v[114:115], v[130:131], v[162:163]
	v_pk_fma_f32 v[164:165], v[116:117], v[132:133], v[164:165]
	s_add_u32 vcc_lo, s18, 0x30000
	s_addc_u32 vcc_hi, s19, 0
	global_store_dwordx4 v154, v[162:165], vcc
	global_load_dwordx4 v[122:125], v[156:157], off offset:64
	s_add_u32 s10, s18, 0xb0000
	s_addc_u32 s11, s19, 0
	global_load_dwordx4 v[150:153], v154, s[10:11] offset:64
	s_waitcnt vmcnt(16)
	v_pk_fma_f32 v[166:167], v[110:111], v[130:131], v[166:167]
	v_pk_fma_f32 v[168:169], v[112:113], v[132:133], v[168:169]
	s_add_u32 vcc_lo, s18, 0x80000
	s_addc_u32 vcc_hi, s19, 0
	global_store_dwordx4 v154, v[166:169], vcc
	global_load_dwordx4 v[118:121], v154, s[18:19] offset:512
	s_waitcnt vmcnt(17)
	v_pk_fma_f32 v[170:171], v[106:107], v[130:131], v[170:171]
	v_pk_fma_f32 v[172:173], v[108:109], v[132:133], v[172:173]
	s_add_u32 vcc_lo, s18, 0x90000
	s_addc_u32 vcc_hi, s19, 0
	global_store_dwordx4 v154, v[170:173], vcc
	s_add_u32 s10, s18, 0x10000
	s_addc_u32 s11, s19, 0
	global_load_dwordx4 v[158:161], v154, s[10:11] offset:512
	s_waitcnt vmcnt(18)
	v_pk_fma_f32 v[174:175], v[102:103], v[130:131], v[174:175]
	v_pk_fma_f32 v[176:177], v[104:105], v[132:133], v[176:177]
	s_add_u32 vcc_lo, s18, 0xa0000
	s_addc_u32 vcc_hi, s19, 0
	global_store_dwordx4 v154, v[174:177], vcc
	s_add_u32 s10, s18, 0x20000
	s_addc_u32 s11, s19, 0
	global_load_dwordx4 v[114:117], v154, s[10:11] offset:512
	s_waitcnt vmcnt(19)
	v_pk_fma_f32 v[178:179], v[98:99], v[130:131], v[178:179]
	v_pk_fma_f32 v[180:181], v[100:101], v[132:133], v[180:181]
	s_add_u32 vcc_lo, s18, 0xb0000
	s_addc_u32 vcc_hi, s19, 0
	global_store_dwordx4 v154, v[178:181], vcc
	s_add_u32 s10, s18, 0x30000
	s_addc_u32 s11, s19, 0
	global_load_dwordx4 v[162:165], v154, s[10:11] offset:512
	s_waitcnt vmcnt(9)
	s_waitcnt vmcnt(20)
	v_pk_fma_f32 v[182:183], v[94:95], v[122:123], v[182:183]
	v_pk_fma_f32 v[184:185], v[96:97], v[124:125], v[184:185]
	global_store_dwordx4 v154, v[182:185], s[18:19] offset:64
	s_add_u32 s10, s18, 0x80000
	s_addc_u32 s11, s19, 0
	global_load_dwordx4 v[110:113], v154, s[10:11] offset:512
	s_waitcnt vmcnt(21)
	v_pk_fma_f32 v[186:187], v[90:91], v[122:123], v[186:187]
	v_pk_fma_f32 v[188:189], v[92:93], v[124:125], v[188:189]
	s_add_u32 vcc_lo, s18, 0x10000
	s_addc_u32 vcc_hi, s19, 0
	global_store_dwordx4 v154, v[186:189], vcc offset:64
	s_add_u32 s10, s18, 0x90000
	s_addc_u32 s11, s19, 0
	global_load_dwordx4 v[166:169], v154, s[10:11] offset:512
	s_waitcnt vmcnt(22)
	v_pk_fma_f32 v[190:191], v[86:87], v[122:123], v[190:191]
	v_pk_fma_f32 v[192:193], v[88:89], v[124:125], v[192:193]
	s_add_u32 vcc_lo, s18, 0x20000
	s_addc_u32 vcc_hi, s19, 0
	global_store_dwordx4 v154, v[190:193], vcc offset:64
	s_add_u32 s10, s18, 0xa0000
	s_addc_u32 s11, s19, 0
	global_load_dwordx4 v[106:109], v154, s[10:11] offset:512
	s_waitcnt vmcnt(23)
	v_pk_fma_f32 v[194:195], v[82:83], v[122:123], v[194:195]
	v_pk_fma_f32 v[196:197], v[84:85], v[124:125], v[196:197]
	s_add_u32 vcc_lo, s18, 0x30000
	s_addc_u32 vcc_hi, s19, 0
	global_store_dwordx4 v154, v[194:197], vcc offset:64
	global_load_dwordx4 v[170:173], v[156:157], off offset:512
	s_add_u32 s10, s18, 0xb0000
	s_addc_u32 s11, s19, 0
	global_load_dwordx4 v[102:105], v154, s[10:11] offset:512
	s_waitcnt vmcnt(24)
	v_pk_fma_f32 v[198:199], v[78:79], v[122:123], v[198:199]
	v_pk_fma_f32 v[200:201], v[80:81], v[124:125], v[200:201]
	s_add_u32 vcc_lo, s18, 0x80000
	s_addc_u32 vcc_hi, s19, 0
	global_store_dwordx4 v154, v[198:201], vcc offset:64
	global_load_dwordx4 v[174:177], v154, s[18:19] offset:576
	s_waitcnt vmcnt(24)
	v_pk_fma_f32 v[126:127], v[74:75], v[122:123], v[126:127]
	v_pk_fma_f32 v[128:129], v[76:77], v[124:125], v[128:129]
	s_add_u32 vcc_lo, s18, 0x90000
	s_addc_u32 vcc_hi, s19, 0
	global_store_dwordx4 v154, v[126:129], vcc offset:64
	s_add_u32 s10, s18, 0x10000
	s_addc_u32 s11, s19, 0
	global_load_dwordx4 v[98:101], v154, s[10:11] offset:576
	s_waitcnt vmcnt(24)
	v_pk_fma_f32 v[142:143], v[70:71], v[122:123], v[142:143]
	v_pk_fma_f32 v[144:145], v[72:73], v[124:125], v[144:145]
	s_add_u32 vcc_lo, s18, 0xa0000
	s_addc_u32 vcc_hi, s19, 0
	global_store_dwordx4 v154, v[142:145], vcc offset:64
	s_add_u32 s10, s18, 0x20000
	s_addc_u32 s11, s19, 0
	global_load_dwordx4 v[178:181], v154, s[10:11] offset:576
	s_waitcnt vmcnt(23)
	v_pk_fma_f32 v[150:151], v[66:67], v[122:123], v[150:151]
	v_pk_fma_f32 v[152:153], v[68:69], v[124:125], v[152:153]
	s_add_u32 vcc_lo, s18, 0xb0000
	s_addc_u32 vcc_hi, s19, 0
	global_store_dwordx4 v154, v[150:153], vcc offset:64
	s_add_u32 s10, s18, 0x30000
	s_addc_u32 s11, s19, 0
	global_load_dwordx4 v[130:133], v154, s[10:11] offset:576
	s_waitcnt vmcnt(9)
	s_waitcnt vmcnt(23)
	v_pk_fma_f32 v[118:119], v[62:63], v[170:171], v[118:119]
	v_pk_fma_f32 v[120:121], v[64:65], v[172:173], v[120:121]
	global_store_dwordx4 v154, v[118:121], s[18:19] offset:512
	s_add_u32 s10, s18, 0x80000
	s_addc_u32 s11, s19, 0
	global_load_dwordx4 v[94:97], v154, s[10:11] offset:576
	s_waitcnt vmcnt(23)
	v_pk_fma_f32 v[158:159], v[58:59], v[170:171], v[158:159]
	v_pk_fma_f32 v[160:161], v[60:61], v[172:173], v[160:161]
	s_add_u32 vcc_lo, s18, 0x10000
	s_addc_u32 vcc_hi, s19, 0
	global_store_dwordx4 v154, v[158:161], vcc offset:512
	s_add_u32 s10, s18, 0x90000
	s_addc_u32 s11, s19, 0
	global_load_dwordx4 v[182:185], v154, s[10:11] offset:576
	s_waitcnt vmcnt(23)
	v_pk_fma_f32 v[114:115], v[54:55], v[170:171], v[114:115]
	v_pk_fma_f32 v[116:117], v[56:57], v[172:173], v[116:117]
	s_add_u32 vcc_lo, s18, 0x20000
	s_addc_u32 vcc_hi, s19, 0
	global_store_dwordx4 v154, v[114:117], vcc offset:512
	s_add_u32 s10, s18, 0xa0000
	s_addc_u32 s11, s19, 0
	global_load_dwordx4 v[90:93], v154, s[10:11] offset:576
	s_waitcnt vmcnt(23)
	v_pk_fma_f32 v[162:163], v[50:51], v[170:171], v[162:163]
	v_pk_fma_f32 v[164:165], v[52:53], v[172:173], v[164:165]
	s_add_u32 vcc_lo, s18, 0x30000
	s_addc_u32 vcc_hi, s19, 0
	global_store_dwordx4 v154, v[162:165], vcc offset:512
	global_load_dwordx4 v[186:189], v[156:157], off offset:576
	s_add_u32 s10, s18, 0xb0000
	s_addc_u32 s11, s19, 0
	global_load_dwordx4 v[86:89], v154, s[10:11] offset:576
	s_waitcnt vmcnt(24)
	v_pk_fma_f32 v[110:111], v[46:47], v[170:171], v[110:111]
	v_pk_fma_f32 v[112:113], v[48:49], v[172:173], v[112:113]
	s_add_u32 vcc_lo, s18, 0x80000
	s_addc_u32 vcc_hi, s19, 0
	global_store_dwordx4 v154, v[110:113], vcc offset:512
	s_waitcnt vmcnt(23)
	v_pk_fma_f32 v[166:167], v[42:43], v[170:171], v[166:167]
	v_pk_fma_f32 v[168:169], v[44:45], v[172:173], v[168:169]
	s_add_u32 vcc_lo, s18, 0x90000
	s_addc_u32 vcc_hi, s19, 0
	global_store_dwordx4 v154, v[166:169], vcc offset:512
	s_waitcnt vmcnt(22)
	v_pk_fma_f32 v[106:107], v[38:39], v[170:171], v[106:107]
	v_pk_fma_f32 v[108:109], v[40:41], v[172:173], v[108:109]
	s_add_u32 vcc_lo, s18, 0xa0000
	s_addc_u32 vcc_hi, s19, 0
	global_store_dwordx4 v154, v[106:109], vcc offset:512
	s_waitcnt vmcnt(20)
	v_pk_fma_f32 v[102:103], v[34:35], v[170:171], v[102:103]
	v_pk_fma_f32 v[104:105], v[36:37], v[172:173], v[104:105]
	s_add_u32 vcc_lo, s18, 0xb0000
	s_addc_u32 vcc_hi, s19, 0
	global_store_dwordx4 v154, v[102:105], vcc offset:512
	s_waitcnt vmcnt(5)
	s_waitcnt vmcnt(19)
	v_pk_fma_f32 v[174:175], v[30:31], v[186:187], v[174:175]
	v_pk_fma_f32 v[176:177], v[32:33], v[188:189], v[176:177]
	global_store_dwordx4 v154, v[174:177], s[18:19] offset:576
	s_waitcnt vmcnt(18)
	v_pk_fma_f32 v[98:99], v[26:27], v[186:187], v[98:99]
	v_pk_fma_f32 v[100:101], v[28:29], v[188:189], v[100:101]
	s_add_u32 vcc_lo, s18, 0x10000
	s_addc_u32 vcc_hi, s19, 0
	global_store_dwordx4 v154, v[98:101], vcc offset:576
	s_waitcnt vmcnt(17)
	v_pk_fma_f32 v[178:179], v[22:23], v[186:187], v[178:179]
	v_pk_fma_f32 v[180:181], v[24:25], v[188:189], v[180:181]
	s_add_u32 vcc_lo, s18, 0x20000
	s_addc_u32 vcc_hi, s19, 0
	global_store_dwordx4 v154, v[178:181], vcc offset:576
	s_waitcnt vmcnt(16)
	v_pk_fma_f32 v[130:131], v[18:19], v[186:187], v[130:131]
	v_pk_fma_f32 v[132:133], v[20:21], v[188:189], v[132:133]
	s_add_u32 vcc_lo, s18, 0x30000
	s_addc_u32 vcc_hi, s19, 0
	global_store_dwordx4 v154, v[130:133], vcc offset:576
	s_waitcnt vmcnt(15)
	v_pk_fma_f32 v[94:95], v[14:15], v[186:187], v[94:95]
	v_pk_fma_f32 v[96:97], v[16:17], v[188:189], v[96:97]
	s_add_u32 vcc_lo, s18, 0x80000
	s_addc_u32 vcc_hi, s19, 0
	global_store_dwordx4 v154, v[94:97], vcc offset:576
	s_waitcnt vmcnt(14)
	v_pk_fma_f32 v[182:183], v[10:11], v[186:187], v[182:183]
	v_pk_fma_f32 v[184:185], v[12:13], v[188:189], v[184:185]
	s_add_u32 vcc_lo, s18, 0x90000
	s_addc_u32 vcc_hi, s19, 0
	global_store_dwordx4 v154, v[182:185], vcc offset:576
	s_waitcnt vmcnt(13)
	v_pk_fma_f32 v[90:91], v[6:7], v[186:187], v[90:91]
	v_pk_fma_f32 v[92:93], v[8:9], v[188:189], v[92:93]
	s_add_u32 vcc_lo, s18, 0xa0000
	s_addc_u32 vcc_hi, s19, 0
	global_store_dwordx4 v154, v[90:93], vcc offset:576
	s_waitcnt vmcnt(11)
	v_pk_fma_f32 v[86:87], v[2:3], v[186:187], v[86:87]
	v_pk_fma_f32 v[88:89], v[4:5], v[188:189], v[88:89]
	s_add_u32 vcc_lo, s18, 0xb0000
	s_addc_u32 vcc_hi, s19, 0
	global_store_dwordx4 v154, v[86:89], vcc offset:576
	s_mov_b64 s[10:11], 0xb0000
	s_mov_b64 s[18:19], -1
	s_and_b64 vcc, exec, s[0:1]
	s_cbranch_vccnz .LBB0_1003
	s_andn2_b64 vcc, exec, s[8:9]
	s_cbranch_vccnz .LBB0_1002
	s_barrier
	s_branch .LBB0_1002
